# up-proj unit loop: wait before the K-loop covers only the prefetched tiles (vmcnt(16)), not the previous epilogue's 16 stores; prologue keeps its full wait (on v78)
# speedup vs baseline: 1.0076x; 1.0076x over previous
; #define PG8_STAGE(bufoff, gbase, voff) do { _Pragma("unroll") for (int _i = 0; _i < 2; ++_i) \
;         __builtin_amdgcn_global_load_lds((const unsigned*)((const char*)(gbase) + (voff)[_i]), (PG8_LAS unsigned*)(lds + (bufoff) + ldsw + _i * 8192), 16, 0, 0); } while (0)
; #define PG8_WAIT_V(n) asm volatile("s_waitcnt vmcnt(" #n ")" ::: "memory")
; #define PG8_BAR __builtin_amdgcn_s_barrier()
; template <class Epi, class Sched, bool ALIGN_EPI = false, bool SP2 = false>
; __device__ __forceinline__ void gemm_phase(PG8_LAS unsigned char* lds, const Gemm g, const Sched& S, const Epi& E) {
;     ...
;     const int tid = tid_, wid = __builtin_amdgcn_readfirstlane(tid >> 6), lane = tid & 63, wr = wid >> 2, wc = wid & 3, fr = lane & 15, fq = lane >> 4;
;     const int K = g.K, nt = K / BK, LD = g.ld;
;     unsigned voffA[2], voffB[2];
; #pragma unroll
;     for (int i = 0; i < 2; ++i) { int R, C; stage_rc(tid * 16 + i * 8192, R, C); const int Rb = Epi::PERM ? ((R & ~31) + perm32(R & 31)) : R;
;         voffA[i] = (unsigned)(R * LD + C) * 2u; voffB[i] = (unsigned)(Rb * LD + C) * 2u; }
;     const size_t kstep = (size_t)(BK * 2);
;     const size_t hstep = (size_t)HALF * LD * 2;
;     const size_t tstep = 2 * hstep;
;     const unsigned ldsw = (unsigned)wid * 1024u;
;     const int aoff = lds_byte(wr * 64 + fr, fq * 8), boff = lds_byte(wc * 32 + fr, fq * 8);
;     ...
;     if constexpr (SP2) {
;         PG8_STAGE(PG8_SB(0, 0), cB, voffB); PG8_STAGE(PG8_SB(0, 1), cB + hstep, voffB); PG8_STAGE(PG8_SA(0, 0), cA, voffA); PG8_STAGE(PG8_SA(0, 1), cA + hstep, voffA);
;         if (wr == 1) PG8_BAR;
;         PG8_WAIT_V(2); PG8_BAR;
;         PG8_STAGE(PG8_SB(1, 0), cB + kstep, voffB); PG8_STAGE(PG8_SA(1, 0), cA + kstep, voffA); PG8_STAGE(PG8_SB(1, 1), cB + hstep + kstep, voffB);
;         PG8_WAIT_V(6); PG8_BAR;
.LBB0_851:
	s_lshl_b32 s0, s0, 5
	s_mov_b64 s[22:23], 0x80
	s_and_b32 s40, s0, 0x60
	s_add_i32 m0, s63, 0x18000
	v_lshl_add_u64 v[6:7], v[6:7], 0, s[22:23]
	s_lshl_b32 s5, s3, 13
	s_lshl_b32 s41, s40, 7
	s_waitcnt vmcnt(2)
	s_barrier
	global_load_lds_dwordx4 v[6:7], off
	v_lshl_add_u64 v[4:5], v[4:5], 0, s[22:23]
	s_add_i32 m0, s63, 0x1a000
	s_add_i32 s68, s63, 0x8000
	s_add_i32 s69, s63, 0xa000
	global_load_lds_dwordx4 v[4:5], off
	v_lshl_add_u64 v[0:1], v[0:1], 0, s[22:23]
	s_mov_b32 m0, s68
	s_add_u32 s24, s58, 0x80080
	global_load_lds_dwordx4 v[0:1], off
	v_lshl_add_u64 v[0:1], v[2:3], 0, s[22:23]
	s_mov_b32 m0, s69
	s_addc_u32 s25, s59, 0
	global_load_lds_dwordx4 v[0:1], off
	s_add_i32 m0, s63, 0x1c000
	v_lshl_add_u64 v[0:1], s[24:25], 0, v[130:131]
	global_load_lds_dwordx4 v[0:1], off
	v_lshl_add_u64 v[0:1], s[24:25], 0, v[134:135]
	s_add_i32 m0, s63, 0x1e000
	s_cmpk_lt_u32 s1, 0x100
	global_load_lds_dwordx4 v[0:1], off
	v_lshrrev_b32_e32 v1, 1, v8
	v_and_b32_e32 v1, 24, v1
	v_and_b32_e32 v0, 15, v8
	v_lshlrev_b32_e32 v2, 1, v1
	v_lshl_or_b32 v152, s3, 6, v0
	v_lshl_or_b32 v0, v0, 6, v2
	v_lshlrev_b32_e32 v2, 2, v8
	v_and_b32_e32 v2, 32, v2
	v_bitop3_b32 v3, v0, s5, v2 bitop3:0xde
	v_bitop3_b32 v153, v0, s41, v2 bitop3:0xde
	v_lshlrev_b32_e32 v0, 15, v9
	v_and_b32_e32 v0, 0xffff0000, v0
	v_or_b32_e32 v154, s40, v1
	v_lshl_add_u32 v0, v10, 12, v0
	v_and_b32_e32 v1, 1, v9
	v_lshl_or_b32 v0, v1, 6, v0
	v_lshl_add_u32 v136, v11, 1, v0
	v_lshlrev_b32_e32 v0, 15, v12
	v_and_b32_e32 v0, 0xffff0000, v0
	s_waitcnt vmcnt(6)
	v_lshl_add_u32 v0, v13, 12, v0
	v_and_b32_e32 v1, 1, v12
	s_cselect_b64 s[24:25], -1, 0
	v_lshl_or_b32 v0, v1, 6, v0
	s_add_i32 s73, 0, 0x10000
	s_add_i32 s74, 0, 0x14000
	s_sext_i32_i8 s0, s2
	v_mov_b32_e32 v137, v131
	v_lshl_add_u32 v138, v14, 1, v0
	v_mov_b32_e32 v139, v131
	v_mov_b64_e32 v[140:141], 0x400
	v_mov_b64_e32 v[142:143], 0x3ff
	v_add_u32_e32 v155, s73, v153
	v_add_u32_e32 v156, s74, v153
	v_add_u32_e32 v157, 0, v3
	v_mov_b32_e32 v158, 0x358637bd
	s_mov_b32 s75, 0xf800000
	v_mov_b32_e32 v159, 0x260
	s_mov_b64 s[40:41], 0x200000
	s_mov_b32 s76, 0x200000
	s_mov_b64 s[42:43], 0x240000
	s_mov_b32 s77, 0x240000
	s_mov_b64 s[44:45], 0x280000
	s_mov_b32 s78, 0x280000
	s_mov_b64 s[46:47], 0x2c0000
	s_mov_b32 s79, 0x2c0000
	s_barrier
	s_waitcnt vmcnt(0)
	s_nop 0
	s_branch .LBB0_854

;     __host__ __device__ bool next(int i, Unit& u) const { if (!StaticOrder::next(i >> 1, u)) return false; u.kh = i & 1; u.slot = i >> 1; return true; }
; template <class Epi, class Sched, bool ALIGN_EPI = false, bool SP2 = false>
; __device__ __forceinline__ void gemm_phase(PG8_LAS unsigned char* lds, const Gemm g, const Sched& S, const Epi& E) {
;     ...
;         const bool has_next = S.next(ui + 1, nxt);
;         const char* nA = has_next ? (const char*)g.A + (size_t)nxt.pm * tstep + nxt.kh * khstep : cA; const char* nB = has_next ? (const char*)g.Bt + (size_t)nxt.pn * tstep + nxt.kh * khstep : cB;
;         for (int t = 0; t < nt; t += 2) {
;             const bool last = (t == nt - 2);
;             const char* a1 = cA + (size_t)(t + 1) * kstep;
;             const char* a2 = last ? nA : cA + (size_t)(t + 2) * kstep; const char* b2 = last ? nB : cB + (size_t)(t + 2) * kstep;
;     ...
; #pragma unroll
;         for (int a = 0; a < 2; ++a)
; #pragma unroll
;             for (int b = 0; b < 2; ++b)
; #pragma unroll
;                 for (int m = 0; m < 4; ++m)
; #pragma unroll
;                     for (int n = 0; n < 2; ++n) acc[a][b][m][n] = (f32x4){0.f, 0.f, 0.f, 0.f};
;         }
;         cur = nxt; cA = nA; cB = nB; ++ui;
.LBB0_860:
	s_ashr_i32 s51, s50, 31
	s_lshl_b64 s[52:53], s[50:51], 20
	s_add_u32 s52, s36, s52
	s_addc_u32 s53, s37, s53
	s_and_b64 s[54:55], s[2:3], exec
	s_cselect_b32 s1, s53, s57
	s_cselect_b32 s5, s52, s56
	s_ashr_i32 s49, s48, 31
	s_lshl_b64 s[54:55], s[48:49], 20
	s_add_u32 s54, s8, s54
	s_addc_u32 s55, s9, s55
	s_and_b64 s[60:61], s[2:3], exec
	s_cselect_b32 s49, s55, s59
	s_cselect_b32 s51, s54, s58
	s_add_u32 s56, s56, 0x80080
	s_addc_u32 s57, s57, 0
	s_add_u32 s80, s58, 0x100
	v_mov_b32_e32 v0, 0
	s_addc_u32 s81, s59, 0
	s_mov_b32 s82, -2
	v_mov_b32_e32 v1, v0
	v_mov_b32_e32 v2, v0
	v_mov_b32_e32 v3, v0
	v_mov_b32_e32 v4, v0
	v_mov_b32_e32 v5, v0
	v_mov_b32_e32 v6, v0
	v_mov_b32_e32 v7, v0
	v_mov_b32_e32 v16, v0
	v_mov_b32_e32 v17, v0
	v_mov_b32_e32 v18, v0
	v_mov_b32_e32 v19, v0
	v_mov_b32_e32 v20, v0
	v_mov_b32_e32 v21, v0
	v_mov_b32_e32 v22, v0
	v_mov_b32_e32 v23, v0
	v_mov_b32_e32 v32, v0
	v_mov_b32_e32 v33, v0
	v_mov_b32_e32 v34, v0
	v_mov_b32_e32 v35, v0
	v_mov_b32_e32 v36, v0
	v_mov_b32_e32 v37, v0
	v_mov_b32_e32 v38, v0
	v_mov_b32_e32 v39, v0
	v_mov_b32_e32 v48, v0
	v_mov_b32_e32 v49, v0
	v_mov_b32_e32 v50, v0
	v_mov_b32_e32 v51, v0
	v_mov_b32_e32 v52, v0
	v_mov_b32_e32 v53, v0
	v_mov_b32_e32 v54, v0
	v_mov_b32_e32 v55, v0
	v_mov_b32_e32 v8, v0
	v_mov_b32_e32 v9, v0
	v_mov_b32_e32 v10, v0
	v_mov_b32_e32 v11, v0
	v_mov_b32_e32 v12, v0
	v_mov_b32_e32 v13, v0
	v_mov_b32_e32 v14, v0
	v_mov_b32_e32 v15, v0
	s_waitcnt vmcnt(16)
	v_mov_b32_e32 v24, v0
	v_mov_b32_e32 v25, v0
	v_mov_b32_e32 v26, v0
	v_mov_b32_e32 v27, v0
	v_mov_b32_e32 v28, v0
	v_mov_b32_e32 v29, v0
	v_mov_b32_e32 v30, v0
	v_mov_b32_e32 v31, v0
	v_mov_b32_e32 v40, v0
	v_mov_b32_e32 v41, v0
	v_mov_b32_e32 v42, v0
	v_mov_b32_e32 v43, v0
	v_mov_b32_e32 v44, v0
	v_mov_b32_e32 v45, v0
	v_mov_b32_e32 v46, v0
	v_mov_b32_e32 v47, v0
	v_mov_b32_e32 v56, v0
	v_mov_b32_e32 v57, v0
	v_mov_b32_e32 v58, v0
	v_mov_b32_e32 v59, v0
	v_mov_b32_e32 v60, v0
	v_mov_b32_e32 v61, v0
	v_mov_b32_e32 v62, v0
	v_mov_b32_e32 v63, v0
	v_mov_b32_e32 v64, v0
	v_mov_b32_e32 v65, v0
	v_mov_b32_e32 v66, v0
	v_mov_b32_e32 v67, v0
	v_mov_b32_e32 v68, v0
	v_mov_b32_e32 v69, v0
	v_mov_b32_e32 v70, v0
	v_mov_b32_e32 v71, v0
	v_mov_b32_e32 v80, v0
	v_mov_b32_e32 v81, v0
	v_mov_b32_e32 v82, v0
	v_mov_b32_e32 v83, v0
	v_mov_b32_e32 v84, v0
	v_mov_b32_e32 v85, v0
	v_mov_b32_e32 v86, v0
	v_mov_b32_e32 v87, v0
	v_mov_b32_e32 v96, v0
	v_mov_b32_e32 v97, v0
	v_mov_b32_e32 v98, v0
	v_mov_b32_e32 v99, v0
	v_mov_b32_e32 v100, v0
	v_mov_b32_e32 v101, v0
	v_mov_b32_e32 v102, v0
	v_mov_b32_e32 v103, v0
	v_mov_b32_e32 v112, v0
	v_mov_b32_e32 v113, v0
	v_mov_b32_e32 v114, v0
	v_mov_b32_e32 v115, v0
	v_mov_b32_e32 v116, v0
	v_mov_b32_e32 v117, v0
	v_mov_b32_e32 v118, v0
	v_mov_b32_e32 v119, v0
	v_mov_b32_e32 v72, v0
	v_mov_b32_e32 v73, v0
	v_mov_b32_e32 v74, v0
	v_mov_b32_e32 v75, v0
	v_mov_b32_e32 v76, v0
	v_mov_b32_e32 v77, v0
	v_mov_b32_e32 v78, v0
	v_mov_b32_e32 v79, v0
	v_mov_b32_e32 v88, v0
	v_mov_b32_e32 v89, v0
	v_mov_b32_e32 v90, v0
	v_mov_b32_e32 v91, v0
	v_mov_b32_e32 v92, v0
	v_mov_b32_e32 v93, v0
	v_mov_b32_e32 v94, v0
	v_mov_b32_e32 v95, v0
	v_mov_b32_e32 v104, v0
	v_mov_b32_e32 v105, v0
	v_mov_b32_e32 v106, v0
	v_mov_b32_e32 v107, v0
	v_mov_b32_e32 v108, v0
	v_mov_b32_e32 v109, v0
	v_mov_b32_e32 v110, v0
	v_mov_b32_e32 v111, v0
	v_mov_b32_e32 v120, v0
	v_mov_b32_e32 v121, v0
	v_mov_b32_e32 v122, v0
	v_mov_b32_e32 v123, v0
	v_mov_b32_e32 v124, v0
	v_mov_b32_e32 v125, v0
	v_mov_b32_e32 v126, v0
	v_mov_b32_e32 v127, v0

; #define PG8_STAGE(bufoff, gbase, voff) do { _Pragma("unroll") for (int _i = 0; _i < 2; ++_i) \
;         __builtin_amdgcn_global_load_lds((const unsigned*)((const char*)(gbase) + (voff)[_i]), (PG8_LAS unsigned*)(lds + (bufoff) + ldsw + _i * 8192), 16, 0, 0); } while (0)
; #define PG8_WAIT_V(n) asm volatile("s_waitcnt vmcnt(" #n ")" ::: "memory")
; #define PG8_BAR __builtin_amdgcn_s_barrier()
; template <class Epi, class Sched, bool ALIGN_EPI = false, bool SP2 = false>
; __device__ __forceinline__ void gemm_phase(PG8_LAS unsigned char* lds, const Gemm g, const Sched& S, const Epi& E) {
;     ...
;     const int tid = tid_, wid = __builtin_amdgcn_readfirstlane(tid >> 6), lane = tid & 63, wr = wid >> 2, wc = wid & 3, fr = lane & 15, fq = lane >> 4;
;     const int K = g.K, nt = K / BK, LD = g.ld;
;     unsigned voffA[2], voffB[2];
; #pragma unroll
;     for (int i = 0; i < 2; ++i) { int R, C; stage_rc(tid * 16 + i * 8192, R, C); const int Rb = Epi::PERM ? ((R & ~31) + perm32(R & 31)) : R;
;         voffA[i] = (unsigned)(R * LD + C) * 2u; voffB[i] = (unsigned)(Rb * LD + C) * 2u; }
;     const size_t kstep = (size_t)(BK * 2);
;     const size_t hstep = (size_t)HALF * LD * 2;
;     const size_t tstep = 2 * hstep;
;     const unsigned ldsw = (unsigned)wid * 1024u;
;     const int aoff = lds_byte(wr * 64 + fr, fq * 8), boff = lds_byte(wc * 32 + fr, fq * 8);
;     ...
;     if constexpr (SP2) {
;         PG8_STAGE(PG8_SB(0, 0), cB, voffB); PG8_STAGE(PG8_SB(0, 1), cB + hstep, voffB); PG8_STAGE(PG8_SA(0, 0), cA, voffA); PG8_STAGE(PG8_SA(0, 1), cA + hstep, voffA);
;         if (wr == 1) PG8_BAR;
;         PG8_WAIT_V(2); PG8_BAR;
;         PG8_STAGE(PG8_SB(1, 0), cB + kstep, voffB); PG8_STAGE(PG8_SA(1, 0), cA + kstep, voffA); PG8_STAGE(PG8_SB(1, 1), cB + hstep + kstep, voffB);
;         PG8_WAIT_V(6); PG8_BAR;
.LBB0_1051:
	s_add_u32 s24, s28, 0x28000
	s_addc_u32 s25, s29, 0
	s_lshl_b32 s0, s0, 5
	s_mov_b64 s[36:37], 0x80
	s_and_b32 s40, s0, 0x60
	s_add_i32 m0, s63, 0x18000
	v_lshl_add_u64 v[6:7], v[6:7], 0, s[36:37]
	s_lshl_b32 s7, s5, 13
	s_lshl_b32 s41, s40, 7
	s_waitcnt vmcnt(2)
	s_barrier
	global_load_lds_dwordx4 v[6:7], off
	v_lshl_add_u64 v[4:5], v[4:5], 0, s[36:37]
	s_add_i32 m0, s63, 0x1a000
	s_add_i32 s68, s63, 0x8000
	s_add_i32 s69, s63, 0xa000
	global_load_lds_dwordx4 v[4:5], off
	v_lshl_add_u64 v[0:1], v[0:1], 0, s[36:37]
	s_mov_b32 m0, s68
	s_add_u32 s38, s58, 0x80080
	global_load_lds_dwordx4 v[0:1], off
	v_lshl_add_u64 v[0:1], v[2:3], 0, s[36:37]
	s_mov_b32 m0, s69
	s_addc_u32 s39, s59, 0
	global_load_lds_dwordx4 v[0:1], off
	s_add_i32 m0, s63, 0x1c000
	v_lshl_add_u64 v[0:1], s[38:39], 0, v[130:131]
	global_load_lds_dwordx4 v[0:1], off
	v_lshl_add_u64 v[0:1], s[38:39], 0, v[134:135]
	s_add_i32 m0, s63, 0x1e000
	s_cmpk_lt_u32 s1, 0x100
	global_load_lds_dwordx4 v[0:1], off
	v_lshrrev_b32_e32 v1, 1, v8
	v_and_b32_e32 v1, 24, v1
	v_and_b32_e32 v0, 15, v8
	v_lshlrev_b32_e32 v2, 1, v1
	v_lshl_or_b32 v152, s5, 6, v0
	v_lshl_or_b32 v0, v0, 6, v2
	v_lshlrev_b32_e32 v2, 2, v8
	v_and_b32_e32 v2, 32, v2
	v_bitop3_b32 v3, v0, s7, v2 bitop3:0xde
	v_bitop3_b32 v153, v0, s41, v2 bitop3:0xde
	v_lshlrev_b32_e32 v0, 15, v9
	v_and_b32_e32 v0, 0xffff0000, v0
	v_or_b32_e32 v154, s40, v1
	v_lshl_add_u32 v0, v10, 12, v0
	v_and_b32_e32 v1, 1, v9
	v_lshl_or_b32 v0, v1, 6, v0
	v_lshl_add_u32 v136, v11, 1, v0
	v_lshlrev_b32_e32 v0, 15, v12
	v_and_b32_e32 v0, 0xffff0000, v0
	s_waitcnt vmcnt(6)
	v_lshl_add_u32 v0, v13, 12, v0
	v_and_b32_e32 v1, 1, v12
	s_cselect_b64 s[38:39], -1, 0
	v_lshl_or_b32 v0, v1, 6, v0
	s_add_i32 s75, 0, 0x10000
	s_add_i32 s76, 0, 0x14000
	s_sext_i32_i8 s0, s4
	v_mov_b32_e32 v137, v131
	v_lshl_add_u32 v138, v14, 1, v0
	v_mov_b32_e32 v139, v131
	v_mov_b64_e32 v[140:141], 0x400
	v_mov_b64_e32 v[142:143], 0x3ff
	v_add_u32_e32 v155, s75, v153
	v_add_u32_e32 v156, s76, v153
	v_add_u32_e32 v157, 0, v3
	v_mov_b32_e32 v158, 0x358637bd
	s_mov_b32 s77, 0xf800000
	v_mov_b32_e32 v159, 0x260
	s_mov_b64 s[40:41], 0x200000
	s_mov_b32 s78, 0x200000
	s_mov_b64 s[42:43], 0x240000
	s_mov_b32 s79, 0x240000
	s_mov_b64 s[44:45], 0x280000
	s_mov_b32 s80, 0x280000
	s_mov_b64 s[46:47], 0x2c0000
	s_mov_b32 s81, 0x2c0000
	s_barrier
	s_waitcnt vmcnt(0)
	s_nop 0
	s_branch .LBB0_1054

;     __host__ __device__ bool next(int i, Unit& u) const { if (!StaticOrder::next(i >> 1, u)) return false; u.kh = i & 1; u.slot = i >> 1; return true; }
; template <class Epi, class Sched, bool ALIGN_EPI = false, bool SP2 = false>
; __device__ __forceinline__ void gemm_phase(PG8_LAS unsigned char* lds, const Gemm g, const Sched& S, const Epi& E) {
;     ...
;         const bool has_next = S.next(ui + 1, nxt);
;         const char* nA = has_next ? (const char*)g.A + (size_t)nxt.pm * tstep + nxt.kh * khstep : cA; const char* nB = has_next ? (const char*)g.Bt + (size_t)nxt.pn * tstep + nxt.kh * khstep : cB;
;         for (int t = 0; t < nt; t += 2) {
;             const bool last = (t == nt - 2);
;             const char* a1 = cA + (size_t)(t + 1) * kstep;
;             const char* a2 = last ? nA : cA + (size_t)(t + 2) * kstep; const char* b2 = last ? nB : cB + (size_t)(t + 2) * kstep;
;     ...
; #pragma unroll
;         for (int a = 0; a < 2; ++a)
; #pragma unroll
;             for (int b = 0; b < 2; ++b)
; #pragma unroll
;                 for (int m = 0; m < 4; ++m)
; #pragma unroll
;                     for (int n = 0; n < 2; ++n) acc[a][b][m][n] = (f32x4){0.f, 0.f, 0.f, 0.f};
;         }
;         cur = nxt; cA = nA; cB = nB; ++ui;
.LBB0_1060:
	s_ashr_i32 s51, s50, 31
	s_lshl_b64 s[52:53], s[50:51], 20
	s_add_u32 s52, s20, s52
	s_addc_u32 s53, s21, s53
	s_and_b64 s[54:55], s[4:5], exec
	s_cselect_b32 s1, s53, s57
	s_cselect_b32 s7, s52, s56
	s_ashr_i32 s49, s48, 31
	s_lshl_b64 s[54:55], s[48:49], 20
	s_add_u32 s54, s8, s54
	s_addc_u32 s55, s9, s55
	s_and_b64 s[60:61], s[4:5], exec
	s_cselect_b32 s49, s55, s59
	s_cselect_b32 s51, s54, s58
	s_add_u32 s56, s56, 0x80080
	s_addc_u32 s57, s57, 0
	s_add_u32 s82, s58, 0x100
	v_mov_b32_e32 v0, 0
	s_addc_u32 s83, s59, 0
	s_mov_b32 s84, -2
	v_mov_b32_e32 v1, v0
	v_mov_b32_e32 v2, v0
	v_mov_b32_e32 v3, v0
	v_mov_b32_e32 v4, v0
	v_mov_b32_e32 v5, v0
	v_mov_b32_e32 v6, v0
	v_mov_b32_e32 v7, v0
	v_mov_b32_e32 v16, v0
	v_mov_b32_e32 v17, v0
	v_mov_b32_e32 v18, v0
	v_mov_b32_e32 v19, v0
	v_mov_b32_e32 v20, v0
	v_mov_b32_e32 v21, v0
	v_mov_b32_e32 v22, v0
	v_mov_b32_e32 v23, v0
	v_mov_b32_e32 v32, v0
	v_mov_b32_e32 v33, v0
	v_mov_b32_e32 v34, v0
	v_mov_b32_e32 v35, v0
	v_mov_b32_e32 v36, v0
	v_mov_b32_e32 v37, v0
	v_mov_b32_e32 v38, v0
	v_mov_b32_e32 v39, v0
	v_mov_b32_e32 v48, v0
	v_mov_b32_e32 v49, v0
	v_mov_b32_e32 v50, v0
	v_mov_b32_e32 v51, v0
	v_mov_b32_e32 v52, v0
	v_mov_b32_e32 v53, v0
	v_mov_b32_e32 v54, v0
	v_mov_b32_e32 v55, v0
	v_mov_b32_e32 v8, v0
	v_mov_b32_e32 v9, v0
	v_mov_b32_e32 v10, v0
	v_mov_b32_e32 v11, v0
	v_mov_b32_e32 v12, v0
	v_mov_b32_e32 v13, v0
	v_mov_b32_e32 v14, v0
	v_mov_b32_e32 v15, v0
	s_waitcnt vmcnt(16)
	v_mov_b32_e32 v24, v0
	v_mov_b32_e32 v25, v0
	v_mov_b32_e32 v26, v0
	v_mov_b32_e32 v27, v0
	v_mov_b32_e32 v28, v0
	v_mov_b32_e32 v29, v0
	v_mov_b32_e32 v30, v0
	v_mov_b32_e32 v31, v0
	v_mov_b32_e32 v40, v0
	v_mov_b32_e32 v41, v0
	v_mov_b32_e32 v42, v0
	v_mov_b32_e32 v43, v0
	v_mov_b32_e32 v44, v0
	v_mov_b32_e32 v45, v0
	v_mov_b32_e32 v46, v0
	v_mov_b32_e32 v47, v0
	v_mov_b32_e32 v56, v0
	v_mov_b32_e32 v57, v0
	v_mov_b32_e32 v58, v0
	v_mov_b32_e32 v59, v0
	v_mov_b32_e32 v60, v0
	v_mov_b32_e32 v61, v0
	v_mov_b32_e32 v62, v0
	v_mov_b32_e32 v63, v0
	v_mov_b32_e32 v64, v0
	v_mov_b32_e32 v65, v0
	v_mov_b32_e32 v66, v0
	v_mov_b32_e32 v67, v0
	v_mov_b32_e32 v68, v0
	v_mov_b32_e32 v69, v0
	v_mov_b32_e32 v70, v0
	v_mov_b32_e32 v71, v0
	v_mov_b32_e32 v80, v0
	v_mov_b32_e32 v81, v0
	v_mov_b32_e32 v82, v0
	v_mov_b32_e32 v83, v0
	v_mov_b32_e32 v84, v0
	v_mov_b32_e32 v85, v0
	v_mov_b32_e32 v86, v0
	v_mov_b32_e32 v87, v0
	v_mov_b32_e32 v96, v0
	v_mov_b32_e32 v97, v0
	v_mov_b32_e32 v98, v0
	v_mov_b32_e32 v99, v0
	v_mov_b32_e32 v100, v0
	v_mov_b32_e32 v101, v0
	v_mov_b32_e32 v102, v0
	v_mov_b32_e32 v103, v0
	v_mov_b32_e32 v112, v0
	v_mov_b32_e32 v113, v0
	v_mov_b32_e32 v114, v0
	v_mov_b32_e32 v115, v0
	v_mov_b32_e32 v116, v0
	v_mov_b32_e32 v117, v0
	v_mov_b32_e32 v118, v0
	v_mov_b32_e32 v119, v0
	v_mov_b32_e32 v72, v0
	v_mov_b32_e32 v73, v0
	v_mov_b32_e32 v74, v0
	v_mov_b32_e32 v75, v0
	v_mov_b32_e32 v76, v0
	v_mov_b32_e32 v77, v0
	v_mov_b32_e32 v78, v0
	v_mov_b32_e32 v79, v0
	v_mov_b32_e32 v88, v0
	v_mov_b32_e32 v89, v0
	v_mov_b32_e32 v90, v0
	v_mov_b32_e32 v91, v0
	v_mov_b32_e32 v92, v0
	v_mov_b32_e32 v93, v0
	v_mov_b32_e32 v94, v0
	v_mov_b32_e32 v95, v0
	v_mov_b32_e32 v104, v0
	v_mov_b32_e32 v105, v0
	v_mov_b32_e32 v106, v0
	v_mov_b32_e32 v107, v0
	v_mov_b32_e32 v108, v0
	v_mov_b32_e32 v109, v0
	v_mov_b32_e32 v110, v0
	v_mov_b32_e32 v111, v0
	v_mov_b32_e32 v120, v0
	v_mov_b32_e32 v121, v0
	v_mov_b32_e32 v122, v0
	v_mov_b32_e32 v123, v0
	v_mov_b32_e32 v124, v0
	v_mov_b32_e32 v125, v0
	v_mov_b32_e32 v126, v0
	v_mov_b32_e32 v127, v0
